# keep_v13 plus tile4 sub-tile 0 K fragment reads pipelined 4 ahead via 6-buffer ring (address adds hoisted to block top)
# baseline (speedup 1.0000x reference)
.LBB0_1038:
	v_add_u32_e32 v231, v210, v180
	v_add_u32_e32 v230, v210, v181
	v_add_u32_e32 v229, v210, v182
	v_add_u32_e32 v227, v210, v183
	v_add_u32_e32 v226, v210, v184
	v_add_u32_e32 v225, v210, v185
	v_add_u32_e32 v224, v210, v186
	v_add_u32_e32 v2, v210, v187
	ds_read_b128 v[36:39], v231
	ds_read_b128 v[40:43], v231 offset:8192
	ds_read_b128 v[44:47], v230
	ds_read_b128 v[244:247], v230 offset:8192
	ds_read_b128 v[248:251], v229
	ds_read_b128 v[252:255], v229 offset:8192
	s_waitcnt vmcnt(7)
	s_waitcnt lgkmcnt(5)
	v_mfma_f32_32x32x16_bf16 v[20:35], v[36:39], v[160:163], 0
	s_cmp_eq_u64 exec, 0
	s_cselect_b64 vcc, -1, 0
	s_waitcnt lgkmcnt(4)
	v_mfma_f32_32x32x16_bf16 v[4:19], v[40:43], v[160:163], 0
	s_waitcnt vmcnt(6)
	ds_read_b128 v[36:39], v227
	s_waitcnt lgkmcnt(4)
	v_mfma_f32_32x32x16_bf16 v[20:35], v[44:47], v[156:159], v[20:35]
	ds_read_b128 v[40:43], v227 offset:8192
	s_waitcnt lgkmcnt(4)
	v_mfma_f32_32x32x16_bf16 v[4:19], v[244:247], v[156:159], v[4:19]
	s_waitcnt vmcnt(5)
	ds_read_b128 v[44:47], v226
	s_waitcnt lgkmcnt(4)
	v_mfma_f32_32x32x16_bf16 v[20:35], v[248:251], v[152:155], v[20:35]
	ds_read_b128 v[244:247], v226 offset:8192
	s_waitcnt lgkmcnt(4)
	v_mfma_f32_32x32x16_bf16 v[4:19], v[252:255], v[152:155], v[4:19]
	s_waitcnt vmcnt(4)
	ds_read_b128 v[248:251], v225
	s_waitcnt lgkmcnt(4)
	v_mfma_f32_32x32x16_bf16 v[20:35], v[36:39], v[148:151], v[20:35]
	ds_read_b128 v[252:255], v225 offset:8192
	s_waitcnt lgkmcnt(4)
	v_mfma_f32_32x32x16_bf16 v[4:19], v[40:43], v[148:151], v[4:19]
	s_waitcnt vmcnt(3)
	ds_read_b128 v[36:39], v224
	s_waitcnt lgkmcnt(4)
	v_mfma_f32_32x32x16_bf16 v[20:35], v[44:47], v[144:147], v[20:35]
	ds_read_b128 v[40:43], v2
	s_waitcnt lgkmcnt(4)
	v_mfma_f32_32x32x16_bf16 v[4:19], v[244:247], v[144:147], v[4:19]
	s_waitcnt vmcnt(2)
	ds_read_b128 v[44:47], v224 offset:8192
	s_waitcnt lgkmcnt(4)
	v_mfma_f32_32x32x16_bf16 v[20:35], v[248:251], v[140:143], v[20:35]
	ds_read_b128 v[244:247], v2 offset:8192
	s_waitcnt lgkmcnt(4)
	v_mfma_f32_32x32x16_bf16 v[4:19], v[252:255], v[140:143], v[4:19]
	s_waitcnt vmcnt(1)
	s_waitcnt lgkmcnt(3)
	v_mfma_f32_32x32x16_bf16 v[20:35], v[36:39], v[136:139], v[20:35]
	s_waitcnt vmcnt(0)
	s_waitcnt lgkmcnt(2)
	v_mfma_f32_32x32x16_bf16 v[20:35], v[40:43], v[132:135], v[20:35]
	s_waitcnt lgkmcnt(1)
	v_mfma_f32_32x32x16_bf16 v[4:19], v[44:47], v[136:139], v[4:19]
	s_nop 10
	v_max_f32_e32 v36, v21, v21
	v_max_f32_e32 v37, v20, v20
	v_max_f32_e32 v36, v37, v36
	v_max3_f32 v36, v36, v22, v23
	v_max3_f32 v36, v36, v24, v25
	v_max3_f32 v36, v36, v26, v27
	v_max3_f32 v36, v36, v28, v29
	s_waitcnt lgkmcnt(0)
	v_mfma_f32_32x32x16_bf16 v[4:19], v[244:247], v[132:135], v[4:19]
	v_max3_f32 v36, v36, v30, v31
	v_max3_f32 v36, v36, v32, v33
	v_max3_f32 v36, v36, v34, v35
	s_nop 8
	v_max3_f32 v36, v36, v4, v5
	v_max3_f32 v36, v36, v6, v7
	v_max3_f32 v36, v36, v8, v9
	v_max3_f32 v36, v36, v10, v11
	v_max3_f32 v36, v36, v12, v13
	v_max3_f32 v36, v36, v14, v15
	v_max3_f32 v36, v36, v16, v17
	v_max3_f32 v36, v36, v18, v19
	v_mov_b32_e32 v37, v36
	s_nop 1
	v_permlane32_swap_b32_e32 v36, v37
	v_max_f32_e32 v37, v37, v37
	v_max_f32_e32 v36, v36, v36
	v_max_f32_e32 v36, v36, v37
	v_add_f32_e32 v37, 0, v36
	v_cndmask_b32_e32 v222, v37, v220, vcc
	v_cmp_ge_f32_e64 s[12:13], s88, v222
	v_cndmask_b32_e64 v228, v36, 0, vcc
	ds_read_b128 v[36:39], v231 offset:16384
	ds_read_b128 v[40:43], v231 offset:24576
	ds_read_b128 v[44:47], v230 offset:16384
	ds_read_b128 v[48:51], v230 offset:24576
	ds_read_b128 v[52:55], v229 offset:16384
	ds_read_b128 v[56:59], v229 offset:24576
	ds_read_b128 v[60:63], v227 offset:16384
	ds_read_b128 v[64:67], v227 offset:24576
	ds_read_b128 v[68:71], v226 offset:16384
	ds_read_b128 v[72:75], v226 offset:24576
	ds_read_b128 v[76:79], v225 offset:16384
	ds_read_b128 v[80:83], v225 offset:24576
	ds_read_b128 v[84:87], v224 offset:16384
	ds_read_b128 v[88:91], v224 offset:24576
	ds_read_b128 v[92:95], v2 offset:16384
	ds_read_b128 v[96:99], v2 offset:24576
	v_cndmask_b32_e64 v100, -v222, 0, s[12:13]
	v_mov_b32_e32 v101, v100
	v_mov_b32_e32 v102, v100
	v_mov_b32_e32 v103, v100
	v_mov_b32_e32 v104, v100
	v_mov_b32_e32 v105, v100
	v_mov_b32_e32 v106, v100
	v_mov_b32_e32 v107, v100
	v_mov_b32_e32 v108, v100
	v_mov_b32_e32 v109, v100
	v_mov_b32_e32 v110, v100
	v_mov_b32_e32 v111, v100
	v_mov_b32_e32 v112, v100
	v_mov_b32_e32 v113, v100
	v_mov_b32_e32 v114, v100
	v_mov_b32_e32 v115, v100
	v_sub_f32_e32 v4, v4, v228
	v_exp_f32_e32 v234, v4
	s_waitcnt lgkmcnt(14)
	v_mfma_f32_32x32x16_bf16 v[116:131], v[36:39], v[160:163], v[100:115]
	v_sub_f32_e32 v4, v21, v228
	v_exp_f32_e32 v21, v4
	v_sub_f32_e32 v4, v5, v228
	v_exp_f32_e32 v235, v4
	v_sub_f32_e32 v4, v22, v228
	v_exp_f32_e32 v22, v4
	v_sub_f32_e32 v4, v6, v228
	v_mfma_f32_32x32x16_bf16 v[100:115], v[40:43], v[160:163], v[100:115]
	v_exp_f32_e32 v236, v4
	v_sub_f32_e32 v4, v23, v228
	v_exp_f32_e32 v23, v4
	v_sub_f32_e32 v4, v7, v228
	v_exp_f32_e32 v237, v4
	v_sub_f32_e32 v4, v24, v228
	v_exp_f32_e32 v6, v4
	s_waitcnt lgkmcnt(13)
	v_mfma_f32_32x32x16_bf16 v[116:131], v[44:47], v[156:159], v[116:131]
	v_sub_f32_e32 v4, v8, v228
	v_exp_f32_e32 v8, v4
	v_sub_f32_e32 v4, v25, v228
	v_exp_f32_e32 v7, v4
	v_sub_f32_e32 v4, v9, v228
	v_exp_f32_e32 v9, v4
	v_sub_f32_e32 v4, v26, v228
	s_waitcnt lgkmcnt(12)
	v_mfma_f32_32x32x16_bf16 v[100:115], v[48:51], v[156:159], v[100:115]
	v_exp_f32_e32 v24, v4
	v_sub_f32_e32 v4, v10, v228
	v_exp_f32_e32 v10, v4
	v_sub_f32_e32 v4, v27, v228
	v_exp_f32_e32 v25, v4
	v_sub_f32_e32 v4, v11, v228
	v_exp_f32_e32 v11, v4
	s_waitcnt lgkmcnt(11)
	v_mfma_f32_32x32x16_bf16 v[116:131], v[52:55], v[152:155], v[116:131]
	v_sub_f32_e32 v4, v28, v228
	v_exp_f32_e32 v26, v4
	v_sub_f32_e32 v4, v12, v228
	v_exp_f32_e32 v12, v4
	v_sub_f32_e32 v4, v29, v228
	v_exp_f32_e32 v27, v4
	v_sub_f32_e32 v4, v13, v228
	s_waitcnt lgkmcnt(10)
	v_mfma_f32_32x32x16_bf16 v[100:115], v[56:59], v[152:155], v[100:115]
	v_exp_f32_e32 v13, v4
	v_sub_f32_e32 v4, v30, v228
	v_exp_f32_e32 v28, v4
	v_sub_f32_e32 v4, v14, v228
	v_exp_f32_e32 v14, v4
	v_sub_f32_e32 v4, v31, v228
	v_exp_f32_e32 v29, v4
	s_waitcnt lgkmcnt(9)
	v_mfma_f32_32x32x16_bf16 v[116:131], v[60:63], v[148:151], v[116:131]
	v_sub_f32_e32 v4, v15, v228
	v_exp_f32_e32 v15, v4
	v_sub_f32_e32 v4, v32, v228
	v_sub_f32_e32 v5, v34, v228
	v_exp_f32_e32 v30, v4
	v_sub_f32_e32 v4, v16, v228
	v_exp_f32_e32 v32, v5
	s_waitcnt lgkmcnt(8)
	v_mfma_f32_32x32x16_bf16 v[100:115], v[64:67], v[148:151], v[100:115]
	v_sub_f32_e32 v5, v18, v228
	v_exp_f32_e32 v16, v4
	v_sub_f32_e32 v4, v33, v228
	v_exp_f32_e32 v18, v5
	v_sub_f32_e32 v5, v35, v228
	v_sub_f32_e32 v20, v20, v228
	v_exp_f32_e32 v31, v4
	s_waitcnt lgkmcnt(7)
	v_mfma_f32_32x32x16_bf16 v[116:131], v[68:71], v[144:147], v[116:131]
	v_sub_f32_e32 v4, v17, v228
	v_exp_f32_e32 v33, v5
	v_sub_f32_e32 v5, v19, v228
	v_exp_f32_e32 v20, v20
	v_exp_f32_e32 v19, v5
	v_exp_f32_e32 v17, v4
	v_pk_add_f32 v[4:5], v[28:29], v[14:15]
	s_waitcnt lgkmcnt(6)
	v_mfma_f32_32x32x16_bf16 v[100:115], v[72:75], v[144:147], v[100:115]
	v_add_f32_e64 v34, v22, v236
	v_add_f32_e64 v35, v23, v237
	v_add_f32_e64 v36, v32, v18
	v_add_f32_e64 v37, v33, v19
	v_add_f32_e64 v38, v24, v10
	v_add_f32_e64 v39, v25, v11
	v_pk_add_f32 v[40:41], v[26:27], v[12:13]
	v_pk_add_f32 v[42:43], v[20:21], v[234:235]
	v_pk_add_f32 v[44:45], v[30:31], v[16:17]
	v_pk_add_f32 v[46:47], v[6:7], v[8:9]
	s_waitcnt lgkmcnt(5)
	v_mfma_f32_32x32x16_bf16 v[116:131], v[76:79], v[140:143], v[116:131]
	v_add_f32_e64 v44, v46, v44
	v_add_f32_e64 v45, v47, v45
	v_add_f32_e64 v40, v42, v40
	v_add_f32_e64 v41, v43, v41
	v_add_f32_e64 v36, v38, v36
	v_add_f32_e64 v37, v39, v37
	v_pk_add_f32 v[4:5], v[34:35], v[4:5]
	v_pk_add_f32 v[34:35], v[40:41], v[44:45]
	v_pk_add_f32 v[4:5], v[4:5], v[36:37]
	s_waitcnt lgkmcnt(4)
	v_mfma_f32_32x32x16_bf16 v[100:115], v[80:83], v[140:143], v[100:115]
	v_pk_mov_b32 v[36:37], v[34:35], v[4:5] op_sel:[1,0]
	v_mov_b32_e32 v35, v5
	v_pk_add_f32 v[4:5], v[36:37], v[34:35]
	s_nop 0
	v_pk_add_f32 v[4:5], v[4:5], v[4:5] op_sel:[0,1] op_sel_hi:[1,0]
	s_nop 0
	v_mov_b32_e32 v5, v4
	s_waitcnt lgkmcnt(3)
	v_mfma_f32_32x32x16_bf16 v[116:131], v[84:87], v[136:139], v[116:131]
	v_permlane32_swap_b32_e32 v4, v5
	v_add_f32_e32 v4, v4, v5
	v_add_f32_e32 v232, 0, v4
	v_cvt_pk_bf16_f32 v4, v20, v21
	v_cvt_pk_bf16_f32 v5, v22, v23
	v_cvt_pk_bf16_f32 v6, v6, v7
	s_waitcnt lgkmcnt(2)
	v_mfma_f32_32x32x16_bf16 v[100:115], v[88:91], v[136:139], v[100:115]
	v_cvt_pk_bf16_f32 v7, v24, v25
	v_cvt_pk_bf16_f32 v68, v26, v27
	v_cvt_pk_bf16_f32 v69, v28, v29
	v_cvt_pk_bf16_f32 v70, v30, v31
	v_cvt_pk_bf16_f32 v71, v32, v33
	v_cvt_pk_bf16_f32 v72, v234, v235
	v_cvt_pk_bf16_f32 v73, v236, v237
	v_cvt_pk_bf16_f32 v74, v8, v9
	v_cvt_pk_bf16_f32 v75, v10, v11
	v_cvt_pk_bf16_f32 v76, v12, v13
	v_cvt_pk_bf16_f32 v77, v14, v15
	v_cvt_pk_bf16_f32 v78, v16, v17
	v_cvt_pk_bf16_f32 v79, v18, v19
	ds_read_b64_tr_b16 v[8:9], v178 offset:0
	ds_read_b64_tr_b16 v[10:11], v178 offset:0x800
	ds_read_b64_tr_b16 v[12:13], v178 offset:0x1000
	s_waitcnt lgkmcnt(1)
	v_mfma_f32_32x32x16_bf16 v[116:131], v[92:95], v[132:135], v[116:131]
	ds_read_b64_tr_b16 v[14:15], v178 offset:0x1800
	ds_read_b64_tr_b16 v[16:17], v178 offset:0x2000
	ds_read_b64_tr_b16 v[18:19], v178 offset:0x2800
	ds_read_b64_tr_b16 v[20:21], v178 offset:0x3000
	ds_read_b64_tr_b16 v[22:23], v178 offset:0x3800
	s_waitcnt lgkmcnt(0)
	v_permlane32_swap_b32_e32 v4, v6
	s_waitcnt lgkmcnt(0)
	v_mfma_f32_32x32x16_bf16 v[100:115], v[96:99], v[132:135], v[100:115]
	v_permlane32_swap_b32_e32 v5, v7
	v_permlane32_swap_b32_e32 v68, v70
	v_permlane32_swap_b32_e32 v69, v71
	v_permlane32_swap_b32_e32 v72, v74
	v_permlane32_swap_b32_e32 v73, v75
	v_permlane32_swap_b32_e32 v76, v78
	v_permlane32_swap_b32_e32 v77, v79
	v_mfma_f32_32x32x16_bf16 v[52:67], v[8:11], v[4:7], 0
	ds_read_b64_tr_b16 v[8:9], v178 offset:0x200
	ds_read_b64_tr_b16 v[10:11], v178 offset:0xa00
	v_mfma_f32_32x32x16_bf16 v[52:67], v[12:15], v[68:71], v[52:67]
	ds_read_b64_tr_b16 v[12:13], v178 offset:0x1200
	ds_read_b64_tr_b16 v[14:15], v178 offset:0x1a00
	v_mfma_f32_32x32x16_bf16 v[52:67], v[16:19], v[72:75], v[52:67]
	ds_read_b64_tr_b16 v[16:17], v178 offset:0x2200
	ds_read_b64_tr_b16 v[18:19], v178 offset:0x2a00
	ds_read_b64_tr_b16 v[24:25], v178 offset:0x3200
	ds_read_b64_tr_b16 v[26:27], v178 offset:0x3a00
	s_waitcnt lgkmcnt(0)
	v_mfma_f32_32x32x16_bf16 v[52:67], v[20:23], v[76:79], v[52:67]
	v_mfma_f32_32x32x16_bf16 v[36:51], v[8:11], v[4:7], 0
	ds_read_b64_tr_b16 v[8:9], v178 offset:0x400
	ds_read_b64_tr_b16 v[10:11], v178 offset:0xc00
	v_mfma_f32_32x32x16_bf16 v[36:51], v[12:15], v[68:71], v[36:51]
	ds_read_b64_tr_b16 v[12:13], v178 offset:0x1400
	ds_read_b64_tr_b16 v[14:15], v178 offset:0x1c00
	v_mfma_f32_32x32x16_bf16 v[36:51], v[16:19], v[72:75], v[36:51]
	ds_read_b64_tr_b16 v[16:17], v178 offset:0x2400
	ds_read_b64_tr_b16 v[18:19], v178 offset:0x2c00
	ds_read_b64_tr_b16 v[80:81], v178 offset:0x3400
	ds_read_b64_tr_b16 v[82:83], v178 offset:0x3c00
	s_waitcnt lgkmcnt(0)
	v_mfma_f32_32x32x16_bf16 v[36:51], v[24:27], v[76:79], v[36:51]
	v_mfma_f32_32x32x16_bf16 v[20:35], v[8:11], v[4:7], 0
	ds_read_b64_tr_b16 v[8:9], v178 offset:0x600
	ds_read_b64_tr_b16 v[10:11], v178 offset:0xe00
	ds_read_b64_tr_b16 v[84:85], v178 offset:0x1600
	ds_read_b64_tr_b16 v[86:87], v178 offset:0x1e00
	ds_read_b64_tr_b16 v[88:89], v178 offset:0x2600
	ds_read_b64_tr_b16 v[90:91], v178 offset:0x2e00
	ds_read_b64_tr_b16 v[92:93], v178 offset:0x3600
	v_mfma_f32_32x32x16_bf16 v[20:35], v[12:15], v[68:71], v[20:35]
	ds_read_b64_tr_b16 v[94:95], v178 offset:0x3e00
	s_waitcnt lgkmcnt(0)
	v_mfma_f32_32x32x16_bf16 v[20:35], v[16:19], v[72:75], v[20:35]
	v_mfma_f32_32x32x16_bf16 v[20:35], v[80:83], v[76:79], v[20:35]
	v_max_f32_e32 v12, v117, v117
	v_max_f32_e32 v13, v116, v116
	v_max_f32_e32 v12, v13, v12
	v_max3_f32 v12, v12, v118, v119
	v_max3_f32 v80, v12, v120, v121
	v_mfma_f32_32x32x16_bf16 v[4:19], v[8:11], v[4:7], 0
	v_max3_f32 v80, v80, v122, v123
	v_max3_f32 v80, v80, v124, v125
	v_max3_f32 v80, v80, v126, v127
	v_max3_f32 v80, v80, v128, v129
	v_max3_f32 v80, v80, v130, v131
	v_max3_f32 v80, v80, v100, v101
	v_max3_f32 v80, v80, v102, v103
	v_mfma_f32_32x32x16_bf16 v[4:19], v[84:87], v[68:71], v[4:19]
	v_max3_f32 v68, v80, v104, v105
	v_max3_f32 v68, v68, v106, v107
	v_max3_f32 v68, v68, v108, v109
	v_max3_f32 v68, v68, v110, v111
	v_max3_f32 v68, v68, v112, v113
	v_max3_f32 v68, v68, v114, v115
	v_mov_b32_e32 v69, v68
	v_mfma_f32_32x32x16_bf16 v[4:19], v[88:91], v[72:75], v[4:19]
	s_nop 0
	v_permlane32_swap_b32_e32 v68, v69
	v_max_f32_e32 v69, v69, v69
	v_max_f32_e32 v68, v68, v68
	v_max_f32_e32 v68, v68, v69
	v_cmp_lt_f32_e32 vcc, s89, v68
	s_or_b64 vcc, s[12:13], vcc
	v_mfma_f32_32x32x16_bf16 v[4:19], v[92:95], v[76:79], v[4:19]
	s_cbranch_vccz .LBB0_1040
	v_cndmask_b32_e32 v234, 0, v68, vcc
	v_exp_f32_e64 v68, -v234
	v_cndmask_b32_e64 v69, v222, 0, s[12:13]
	v_add_f32_e32 v222, v69, v234
	v_xor_b32_e32 v233, 0x80000000, v222
	v_cndmask_b32_e64 v68, v68, 0, s[12:13]
	v_mul_f32_e32 v232, v232, v68
	v_pk_mul_f32 v[66:67], v[66:67], v[68:69] op_sel_hi:[1,0]
	v_pk_mul_f32 v[64:65], v[64:65], v[68:69] op_sel_hi:[1,0]
	v_pk_mul_f32 v[62:63], v[62:63], v[68:69] op_sel_hi:[1,0]
	v_pk_mul_f32 v[60:61], v[60:61], v[68:69] op_sel_hi:[1,0]
	v_pk_mul_f32 v[58:59], v[58:59], v[68:69] op_sel_hi:[1,0]
	v_pk_mul_f32 v[56:57], v[56:57], v[68:69] op_sel_hi:[1,0]
	v_pk_mul_f32 v[54:55], v[54:55], v[68:69] op_sel_hi:[1,0]
	v_pk_mul_f32 v[52:53], v[52:53], v[68:69] op_sel_hi:[1,0]
	v_pk_mul_f32 v[50:51], v[50:51], v[68:69] op_sel_hi:[1,0]
	v_pk_mul_f32 v[48:49], v[48:49], v[68:69] op_sel_hi:[1,0]
	v_pk_mul_f32 v[46:47], v[46:47], v[68:69] op_sel_hi:[1,0]
	v_pk_mul_f32 v[44:45], v[44:45], v[68:69] op_sel_hi:[1,0]
	v_pk_mul_f32 v[42:43], v[42:43], v[68:69] op_sel_hi:[1,0]
	v_pk_mul_f32 v[40:41], v[40:41], v[68:69] op_sel_hi:[1,0]
	v_pk_mul_f32 v[38:39], v[38:39], v[68:69] op_sel_hi:[1,0]
	v_pk_mul_f32 v[36:37], v[36:37], v[68:69] op_sel_hi:[1,0]
	v_pk_mul_f32 v[34:35], v[34:35], v[68:69] op_sel_hi:[1,0]
	v_pk_mul_f32 v[32:33], v[32:33], v[68:69] op_sel_hi:[1,0]
	v_pk_mul_f32 v[30:31], v[30:31], v[68:69] op_sel_hi:[1,0]
	v_pk_mul_f32 v[28:29], v[28:29], v[68:69] op_sel_hi:[1,0]
	v_pk_mul_f32 v[26:27], v[26:27], v[68:69] op_sel_hi:[1,0]
	v_pk_mul_f32 v[24:25], v[24:25], v[68:69] op_sel_hi:[1,0]
	v_pk_mul_f32 v[22:23], v[22:23], v[68:69] op_sel_hi:[1,0]
	v_pk_mul_f32 v[20:21], v[20:21], v[68:69] op_sel_hi:[1,0]
	v_pk_mul_f32 v[18:19], v[18:19], v[68:69] op_sel_hi:[1,0]
	v_pk_mul_f32 v[16:17], v[16:17], v[68:69] op_sel_hi:[1,0]
	v_pk_mul_f32 v[14:15], v[14:15], v[68:69] op_sel_hi:[1,0]
	v_pk_mul_f32 v[12:13], v[12:13], v[68:69] op_sel_hi:[1,0]
	v_pk_mul_f32 v[10:11], v[10:11], v[68:69] op_sel_hi:[1,0]
	v_pk_mul_f32 v[8:9], v[8:9], v[68:69] op_sel_hi:[1,0]
	v_pk_mul_f32 v[6:7], v[6:7], v[68:69] op_sel_hi:[1,0]
	v_pk_mul_f32 v[4:5], v[4:5], v[68:69] op_sel_hi:[1,0]
	s_branch .LBB0_1041
